# layer-0 sub-key fold GEMM tiles are done two per workgroup by the workgroups that finish the input projection a tile early, none by the others
# baseline (speedup 1.0000x reference)
; __device__ __forceinline__ int otid() { int t = threadIdx.x; asm volatile("" : "+v"(t)); return t; }
; template <int MI, bool SWAP, bool F8 = false>
; __device__ __forceinline__ void gemm_core(const bf16_t* __restrict__ A, int lda, const bf16_t* __restrict__ B, int ldb,
;                                           int K, char* smem, f32x4 (&acc)[MI][4]) {
;   const int tid = otid(), lane = tid & 63, w = tid >> 6, wm = w >> 1, wn = w & 1;
;   const int lr = tid >> 3, lc = tid & 7;
;   const int li = lane & 15, g = lane >> 4;
;   u32x4 ra[MI], rb[4];
;   const bf16_t* ap = A + (size_t)lr * lda + lc * 8;
;   const bf16_t* bp = B + (size_t)lr * ldb + lc * 8;
; #pragma unroll
;   for (int i = 0; i < MI; ++i)
; #pragma unroll
;     for (int j = 0; j < 4; ++j) acc[i][j] = (f32x4){0.f, 0.f, 0.f, 0.f};
;   const int nk = K >> 6;
; #pragma unroll
;   for (int i = 0; i < MI; ++i) ra[i] = *(const u32x4*)(ap + (size_t)(32 * i) * lda);
; #pragma unroll
;   for (int i = 0; i < 4; ++i) rb[i] = *(const u32x4*)(bp + (size_t)(32 * i) * ldb);
;   const int woff = lr * 128 + ((lc ^ (lr & 7)) << 4);
;   const int xrow = (wm * 16 * MI + li) * 128;
;   const int wrow = 32768 + (wn * 32 + li) * 128;
;   for (int kt = 0; kt < nk; ++kt) {
;     __syncthreads();
; #pragma unroll
;     for (int i = 0; i < MI; ++i) *(u32x4*)(smem + woff + i * 4096) = ra[i];
; #pragma unroll
;     for (int i = 0; i < 4; ++i) *(u32x4*)(smem + 32768 + woff + i * 4096) = rb[i];
;     __syncthreads();
; __global__ void __launch_bounds__(256, 2) fwd_kernel(P p) {
;     ...
;       for (int it = blockIdx.x; it < 64 * 28; it += G) even_in_tile(p, li2, (it & 7) * 8 + (it >> 3) / 28, (it >> 3) % 28, smem);
;       if (layer == 0) {
;         for (int it = blockIdx.x; it < 512; it += G) {
;           const int lf = it >> 7, hp = (it >> 3) & 15, kc = it & 7;
;           gemm_tile_fp8out<4>((const bf16_t*)(ws + OFF_SUBK) + ((size_t)lf * 16 + hp) * 16384, 128,
;                               (const bf16_t*)(ws + OFF_AO) + (size_t)lf * 1024 * 2048 + (size_t)(kc * 128) * 2048 + hp * 128, 2048, 128,
;                               (unsigned char*)(ws + OFF_WPQ) + ((size_t)lf * 2048 + hp * 128) * 1024 + kc * 128, 1024, 256.f, smem);
.LBB0_383:
	v_readlane_b32 s0, v255, 60
	v_readlane_b32 s1, v255, 61
	s_cmp_lg_u32 s0, 0
	s_cselect_b64 s[0:1], -1, 0
	s_and_b64 s[6:7], s[0:1], exec
	s_mov_b32 s6, 0xc000
	s_cselect_b32 s19, 0x10000, s6
	s_cselect_b32 s36, s6, 0
	v_readlane_b32 s6, v255, 38
	v_readlane_b32 s7, v255, 39
	s_or_b64 s[0:1], s[0:1], s[6:7]
	s_and_b64 vcc, exec, s[0:1]
	s_cbranch_vccnz .LBB0_387
	s_add_u32 s6, s12, 0x3884000
	s_addc_u32 s7, s13, 0
	s_add_u32 s8, s12, 0x25a84000
	s_addc_u32 s9, s13, 0
	s_add_u32 s10, s12, 0x2884000
	v_readlane_b32 s0, v255, 53
	s_addc_u32 s11, s13, 0
	v_readlane_b32 s19, v255, 52
	s_mov_b32 s20, s0
	s_mov_b32 s27, 0x60000
	s_movk_i32 s28, 0x2000
	s_movk_i32 s29, 0xffc0
	s_movk_i32 s30, 0x4000
	s_mov_b32 s31, 0x1ffffc0
	v_readlane_b32 s1, v255, 54
	s_cmp_lt_u32 s20, 0x100
	s_cbranch_scc1 .Lfold_skip
	s_sub_u32 s20, s20, 0x100
	s_lshl_b32 s19, s20, 7
.LBB0_385:
	s_ashr_i32 s0, s20, 7
	s_ashr_i32 s1, s0, 31
	s_bfe_u32 s21, s20, 0x40003
	s_lshl_b64 s[22:23], s[0:1], 19
	s_add_u32 s22, s6, s22
	s_waitcnt vmcnt(14)
	v_mov_b32_e32 v92, v208
	s_addc_u32 s23, s7, s23
	s_lshl_b32 s24, s21, 15
	s_add_u32 s22, s22, s24
	v_ashrrev_i32_e32 v2, 3, v92
	v_ashrrev_i32_e32 v3, 31, v2
	s_addc_u32 s23, s23, 0
	s_lshl_b64 s[24:25], s[0:1], 22
	v_lshlrev_b32_e32 v0, 4, v92
	v_lshlrev_b32_e32 v23, 7, v2
	v_xor_b32_e32 v24, v2, v92
	v_lshlrev_b64 v[40:41], 12, v[2:3]
	v_lshlrev_b64 v[2:3], 8, v[2:3]
	s_add_u32 s24, s8, s24
	v_and_b32_e32 v21, 15, v92
	v_lshrrev_b32_e32 v22, 1, v92
	v_and_b32_e32 v0, 0x70, v0
	v_lshl_add_u64 v[2:3], s[22:23], 0, v[2:3]
	s_addc_u32 s23, s9, s25
	s_and_b32 s22, s19, 0x380
	v_lshrrev_b32_e32 v20, 4, v92
	v_and_b32_e32 v93, 7, v92
	v_and_or_b32 v25, v22, s31, v21
	v_and_or_b32 v21, v22, 32, v21
	v_lshlrev_b32_e32 v22, 4, v24
	v_lshl_add_u64 v[2:3], v[2:3], 0, v[0:1]
	s_lshl_b32 s25, s22, 12
	v_bitop3_b32 v20, v20, v93, 3 bitop3:0x6c
	v_and_or_b32 v134, v22, s33, v23
	v_add_co_u32_e32 v22, vcc, s28, v2
	s_add_u32 s24, s24, s25
	v_lshlrev_b32_e32 v94, 7, v25
	v_lshlrev_b32_e32 v95, 7, v21
	v_lshlrev_b32_e32 v20, 4, v20
	v_addc_co_u32_e32 v23, vcc, 0, v3, vcc
	s_addc_u32 s23, s23, 0
	s_lshl_b32 s25, s21, 8
	v_or_b32_e32 v135, v95, v20
	v_or_b32_e32 v136, v94, v20
	v_add_co_u32_e32 v20, vcc, s30, v2
	s_add_u32 s24, s24, s25
	s_nop 0
	v_addc_co_u32_e32 v21, vcc, 0, v3, vcc
	s_movk_i32 s26, 0x6000
	s_addc_u32 s25, s23, 0
	s_waitcnt vmcnt(10)
	v_add_co_u32_e32 v120, vcc, s26, v2
	v_lshl_add_u64 v[40:41], s[24:25], 0, v[40:41]
	s_nop 0
	v_addc_co_u32_e32 v121, vcc, 0, v3, vcc
	s_waitcnt vmcnt(9)
	v_lshl_add_u64 v[124:125], v[40:41], 0, v[0:1]
	v_add_co_u32_e32 v126, vcc, s46, v124
	global_load_dwordx4 v[24:27], v[2:3], off
	s_nop 0
	v_addc_co_u32_e32 v127, vcc, 0, v125, vcc
	s_waitcnt vmcnt(9)
	v_add_co_u32_e32 v128, vcc, s50, v124
	global_load_dwordx4 v[28:31], v[22:23], off
	global_load_dwordx4 v[32:35], v[20:21], off
	global_load_dwordx4 v[36:39], v[120:121], off
	v_addc_co_u32_e32 v129, vcc, 0, v125, vcc
	v_add_co_u32_e32 v132, vcc, s27, v124
	v_bfe_u32 v0, v92, 4, 2
	s_nop 0
	v_addc_co_u32_e32 v133, vcc, 0, v125, vcc
	global_load_dwordx4 v[40:43], v[124:125], off
	global_load_dwordx4 v[44:47], v[126:127], off
	global_load_dwordx4 v[48:51], v[128:129], off
	global_load_dwordx4 v[52:55], v[132:133], off
	s_waitcnt vmcnt(63) expcnt(7) lgkmcnt(15)
	s_barrier
	v_bitop3_b32 v0, v0, v93, 4 bitop3:0x36
	v_lshlrev_b32_e32 v0, 4, v0
	v_or_b32_e32 v137, v95, v0
	v_or_b32_e32 v0, v94, v0
	s_lshl_b64 s[0:1], s[0:1], 21
	s_lshl_b32 s21, s21, 17
	s_add_u32 s0, s10, s0
	s_addc_u32 s1, s11, s1
	s_add_u32 s0, s0, s21
	s_addc_u32 s1, s1, 0
	s_add_u32 s0, s0, s22
	s_addc_u32 s1, s1, 0
	s_add_i32 s20, s20, 0x100
	s_add_i32 s19, s19, 0x8000
	s_cmpk_lt_i32 s20, 0x200
	s_waitcnt vmcnt(7)
	ds_write_b128 v134, v[24:27]
	s_waitcnt vmcnt(6)
	ds_write_b128 v134, v[28:31] offset:4096
	s_waitcnt vmcnt(5)
	ds_write_b128 v134, v[32:35] offset:8192
	s_waitcnt vmcnt(4)
	ds_write_b128 v134, v[36:39] offset:12288
	s_waitcnt vmcnt(3)
	ds_write_b128 v134, v[40:43] offset:32768
	s_waitcnt vmcnt(2)
	ds_write_b128 v134, v[44:47] offset:36864
	s_waitcnt vmcnt(1)
	ds_write_b128 v134, v[48:51] offset:40960
	s_waitcnt vmcnt(0)
	ds_write_b128 v134, v[52:55] offset:45056
	s_waitcnt lgkmcnt(0)
	s_barrier
; template <int MI, bool SWAP, bool F8 = false>
; __device__ __forceinline__ void gemm_core(const bf16_t* __restrict__ A, int lda, const bf16_t* __restrict__ B, int ldb,
;                                           int K, char* smem, f32x4 (&acc)[MI][4]) {
;     ...
;   for (int kt = 0; kt < nk; ++kt) {
;     __syncthreads();
; #pragma unroll
;     for (int i = 0; i < MI; ++i) *(u32x4*)(smem + woff + i * 4096) = ra[i];
; #pragma unroll
;     for (int i = 0; i < 4; ++i) *(u32x4*)(smem + 32768 + woff + i * 4096) = rb[i];
;     __syncthreads();
;     if (kt + 1 < nk) {
; #pragma unroll
;       for (int i = 0; i < MI; ++i) ra[i] = *(const u32x4*)(ap + (size_t)(32 * i) * lda + (kt + 1) * 64);
; #pragma unroll
;       for (int i = 0; i < 4; ++i) rb[i] = *(const u32x4*)(bp + (size_t)(32 * i) * ldb + (kt + 1) * 64);
;     }
;     if (F8) {
;       const int c0 = (g ^ (li & 7)) << 4, c1 = ((4 + g) ^ (li & 7)) << 4;
;       i32x8 wf8[4];
; #pragma unroll
;       for (int j = 0; j < 4; ++j) {
;         const char* rp = smem + wrow + ((j & 1) * 16 + (j >> 1) * 64) * 128;
;         const u32x4 lo = *(const u32x4*)(rp + c0), hi = *(const u32x4*)(rp + c1);
;         wf8[j] = (i32x8){(int)lo.x, (int)lo.y, (int)lo.z, (int)lo.w, (int)hi.x, (int)hi.y, (int)hi.z, (int)hi.w};
;       }
; #pragma unroll
;       for (int i = 0; i < MI; ++i) {
;         const char* rp = smem + xrow + i * 2048;
;         const u32x4 lo = *(const u32x4*)(rp + c0), hi = *(const u32x4*)(rp + c1);
;         const i32x8 xf8 = {(int)lo.x, (int)lo.y, (int)lo.z, (int)lo.w, (int)hi.x, (int)hi.y, (int)hi.z, (int)hi.w};
; #pragma unroll
;         for (int j = 0; j < 4; ++j)
;           acc[i][j] = __builtin_amdgcn_mfma_scale_f32_16x16x128_f8f6f4(wf8[j], xf8, acc[i][j], 0, 0, 0, 0x77777777, 0, 0x7f7f7f7f);
;       }
;     } else {
; #pragma unroll
;     for (int kk = 0; kk < 2; ++kk) {
;       const int ch = ((kk * 4 + g) ^ (li & 7)) << 4;
;       bf16x8 xf[MI], wf[4];
; #pragma unroll
;       for (int j = 0; j < 4; ++j) wf[j] = *(const bf16x8*)(smem + wrow + ((j & 1) * 16 + (j >> 1) * 64) * 128 + ch);
; #pragma unroll
;       for (int i = 0; i < MI; ++i) xf[i] = *(const bf16x8*)(smem + xrow + i * 2048 + ch);
; #pragma unroll
;       for (int i = 0; i < MI; ++i)
; #pragma unroll
;         for (int j = 0; j < 4; ++j) {
	ds_read_b128 v[24:27], v135 offset:32768
	ds_read_b128 v[28:31], v135 offset:34816
	ds_read_b128 v[32:35], v136
	ds_read_b128 v[36:39], v136 offset:2048
	ds_read_b128 v[44:47], v135 offset:40960
	ds_read_b128 v[52:55], v135 offset:43008
	ds_read_b128 v[72:75], v136 offset:4096
	ds_read_b128 v[76:79], v136 offset:6144
	s_waitcnt lgkmcnt(5)
	v_mfma_f32_16x16x32_bf16 v[40:43], v[24:27], v[32:35], 0
	ds_read_b128 v[92:95], v137 offset:32768
	ds_read_b128 v[96:99], v137 offset:34816
	v_mfma_f32_16x16x32_bf16 v[48:51], v[28:31], v[32:35], 0
	s_waitcnt lgkmcnt(5)
	v_mfma_f32_16x16x32_bf16 v[56:59], v[44:47], v[32:35], 0
	s_waitcnt lgkmcnt(4)
	v_mfma_f32_16x16x32_bf16 v[32:35], v[52:55], v[32:35], 0
	v_mfma_f32_16x16x32_bf16 v[60:63], v[24:27], v[36:39], 0
	v_mfma_f32_16x16x32_bf16 v[64:67], v[28:31], v[36:39], 0
	v_mfma_f32_16x16x32_bf16 v[68:71], v[44:47], v[36:39], 0
	v_mfma_f32_16x16x32_bf16 v[36:39], v[52:55], v[36:39], 0
	s_waitcnt lgkmcnt(3)
	v_mfma_f32_16x16x32_bf16 v[80:83], v[24:27], v[72:75], 0
	v_mfma_f32_16x16x32_bf16 v[84:87], v[28:31], v[72:75], 0
	v_mfma_f32_16x16x32_bf16 v[88:91], v[44:47], v[72:75], 0
	v_mfma_f32_16x16x32_bf16 v[72:75], v[52:55], v[72:75], 0
	s_waitcnt lgkmcnt(2)
	v_mfma_f32_16x16x32_bf16 v[24:27], v[24:27], v[76:79], 0
	v_mfma_f32_16x16x32_bf16 v[28:31], v[28:31], v[76:79], 0
	v_mfma_f32_16x16x32_bf16 v[44:47], v[44:47], v[76:79], 0
	v_mfma_f32_16x16x32_bf16 v[76:79], v[52:55], v[76:79], 0
	ds_read_b128 v[52:55], v0
	ds_read_b128 v[100:103], v0 offset:2048
	ds_read_b128 v[108:111], v137 offset:43008
	s_waitcnt lgkmcnt(2)
	v_mfma_f32_16x16x32_bf16 v[104:107], v[92:95], v[52:55], v[40:43]
	s_nop 2
	ds_read_b128 v[40:43], v137 offset:40960
	s_waitcnt lgkmcnt(0)
	v_mfma_f32_16x16x32_bf16 v[112:115], v[40:43], v[52:55], v[56:59]
	v_mfma_f32_16x16x32_bf16 v[116:119], v[92:95], v[100:103], v[60:63]
	v_mfma_f32_16x16x32_bf16 v[64:67], v[96:99], v[100:103], v[64:67]
	v_mfma_f32_16x16x32_bf16 v[68:71], v[40:43], v[100:103], v[68:71]
	v_mfma_f32_16x16x32_bf16 v[100:103], v[108:111], v[100:103], v[36:39]
	s_nop 2
	ds_read_b128 v[36:39], v0 offset:4096
	ds_read_b128 v[56:59], v0 offset:6144
	global_load_dwordx4 v[60:63], v[22:23], off offset:128
	s_waitcnt lgkmcnt(1)
	v_mfma_f32_16x16x32_bf16 v[80:83], v[92:95], v[36:39], v[80:83]
	v_mfma_f32_16x16x32_bf16 v[84:87], v[96:99], v[36:39], v[84:87]
	v_mfma_f32_16x16x32_bf16 v[88:91], v[40:43], v[36:39], v[88:91]
	v_mfma_f32_16x16x32_bf16 v[72:75], v[108:111], v[36:39], v[72:75]
	global_load_dwordx4 v[36:39], v[2:3], off offset:128
	s_nop 0
	global_load_dwordx4 v[120:123], v[120:121], off offset:128
	s_nop 0
	global_load_dwordx4 v[20:23], v[20:21], off offset:128
	v_mov_b32_e32 v2, v208
	s_waitcnt lgkmcnt(0)
	v_mfma_f32_16x16x32_bf16 v[92:95], v[92:95], v[56:59], v[24:27]
	s_nop 2
	global_load_dwordx4 v[24:27], v[126:127], off offset:128
	s_nop 0
	global_load_dwordx4 v[124:127], v[124:125], off offset:128
	s_nop 0
	global_load_dwordx4 v[128:131], v[128:129], off offset:128
	v_mfma_f32_16x16x32_bf16 v[48:51], v[96:99], v[52:55], v[48:51]
	v_mfma_f32_16x16x32_bf16 v[32:35], v[108:111], v[52:55], v[32:35]
	v_mfma_f32_16x16x32_bf16 v[52:55], v[96:99], v[56:59], v[28:31]
	s_nop 2
	global_load_dwordx4 v[28:31], v[132:133], off offset:128
	v_mfma_f32_16x16x32_bf16 v[40:43], v[40:43], v[56:59], v[44:47]
	s_barrier
	v_mfma_f32_16x16x32_bf16 v[44:47], v[108:111], v[56:59], v[76:79]
	s_waitcnt vmcnt(6)
	ds_write_b128 v134, v[36:39]
	ds_write_b128 v134, v[60:63] offset:4096
	s_waitcnt vmcnt(4)
	ds_write_b128 v134, v[20:23] offset:8192
	ds_write_b128 v134, v[120:123] offset:12288
	s_waitcnt vmcnt(2)
	ds_write_b128 v134, v[124:127] offset:32768
	ds_write_b128 v134, v[24:27] offset:36864
	s_waitcnt vmcnt(1)
	ds_write_b128 v134, v[128:131] offset:40960
	s_waitcnt vmcnt(0)
	ds_write_b128 v134, v[28:31] offset:45056
	s_waitcnt lgkmcnt(0)
	s_barrier
	ds_read_b128 v[76:79], v135 offset:32768
	ds_read_b128 v[96:99], v135 offset:34816
	ds_read_b128 v[20:23], v136
	ds_read_b128 v[24:27], v136 offset:2048
	s_waitcnt lgkmcnt(1)
	v_mfma_f32_16x16x32_bf16 v[56:59], v[76:79], v[20:23], v[104:107]
	s_nop 2
	ds_read_b128 v[104:107], v135 offset:40960
	ds_read_b128 v[108:111], v135 offset:43008
	v_mov_b32_e32 v120, v1
	v_mfma_f32_16x16x32_bf16 v[60:63], v[96:99], v[20:23], v[48:51]
	v_mov_b32_e32 v121, v1
	v_mov_b32_e32 v122, v1
	v_mov_b32_e32 v123, v1
	s_waitcnt lgkmcnt(0)
	v_mfma_f32_16x16x32_bf16 v[48:51], v[108:111], v[20:23], v[32:35]
	v_mov_b32_e32 v124, v1
	v_mov_b32_e32 v125, v1
	v_mov_b32_e32 v126, v1
	v_mfma_f32_16x16x32_bf16 v[32:35], v[96:99], v[24:27], v[64:67]
	v_mov_b32_e32 v127, v1
	v_mov_b32_e32 v128, v1
	v_mov_b32_e32 v129, v1
	v_mfma_f32_16x16x32_bf16 v[28:31], v[104:107], v[24:27], v[68:71]
	ds_read_b128 v[64:67], v136 offset:4096
	s_nop 1
	ds_read_b128 v[68:71], v136 offset:6144
	v_mov_b32_e32 v130, v1
	v_mov_b32_e32 v131, v1
	v_mfma_f32_16x16x32_bf16 v[112:115], v[104:107], v[20:23], v[112:115]
	v_mfma_f32_16x16x32_bf16 v[36:39], v[76:79], v[24:27], v[116:119]
	v_mfma_f32_16x16x32_bf16 v[24:27], v[108:111], v[24:27], v[100:103]
	s_nop 1
	v_mov_b32_e32 v116, v1
	v_mov_b32_e32 v117, v1
	v_mov_b32_e32 v118, v1
	s_waitcnt lgkmcnt(1)
	v_mfma_f32_16x16x32_bf16 v[20:23], v[76:79], v[64:67], v[80:83]
	v_mov_b32_e32 v119, v1
	v_mfma_f32_16x16x32_bf16 v[80:83], v[96:99], v[64:67], v[84:87]
	v_mfma_f32_16x16x32_bf16 v[84:87], v[104:107], v[64:67], v[88:91]
	v_mfma_f32_16x16x32_bf16 v[64:67], v[108:111], v[64:67], v[72:75]
	s_waitcnt lgkmcnt(0)
; template <int MI, bool SWAP, bool F8 = false>
; __device__ __forceinline__ void gemm_core(const bf16_t* __restrict__ A, int lda, const bf16_t* __restrict__ B, int ldb,
;                                           int K, char* smem, f32x4 (&acc)[MI][4]) {
;     ...
;     for (int kk = 0; kk < 2; ++kk) {
;       const int ch = ((kk * 4 + g) ^ (li & 7)) << 4;
;       bf16x8 xf[MI], wf[4];
; #pragma unroll
;       for (int j = 0; j < 4; ++j) wf[j] = *(const bf16x8*)(smem + wrow + ((j & 1) * 16 + (j >> 1) * 64) * 128 + ch);
; #pragma unroll
;       for (int i = 0; i < MI; ++i) xf[i] = *(const bf16x8*)(smem + xrow + i * 2048 + ch);
; #pragma unroll
;       for (int i = 0; i < MI; ++i)
; #pragma unroll
;         for (int j = 0; j < 4; ++j) {
;           if (SWAP) acc[i][j] = __builtin_amdgcn_mfma_f32_16x16x32_bf16(xf[i], wf[j], acc[i][j], 0, 0, 0);
;           else acc[i][j] = __builtin_amdgcn_mfma_f32_16x16x32_bf16(wf[j], xf[i], acc[i][j], 0, 0, 0);
;         }
; template <int MI>
; __device__ void gemm_tile_fp8out(const bf16_t* A, int lda, const bf16_t* B, int ldb, int K, unsigned char* C, int ldc, float mul, char* smem) {
;     ...
; #pragma unroll
;   for (int i = 0; i < MI; ++i)
; #pragma unroll
;     for (int j = 0; j < 4; ++j) {
;       int wd = __builtin_amdgcn_cvt_pk_fp8_f32(acc[i][j][0] * mul, acc[i][j][1] * mul, 0, false);
;       wd = __builtin_amdgcn_cvt_pk_fp8_f32(acc[i][j][2] * mul, acc[i][j][3] * mul, wd, true);
;       *(int*)(C + (size_t)MROW(i) * ldc + NCOL(j)) = wd;
;     }
	v_mfma_f32_16x16x32_bf16 v[72:75], v[76:79], v[68:71], v[92:95]
	ds_read_b128 v[76:79], v137 offset:32768
	ds_read_b128 v[88:91], v137 offset:34816
	v_mfma_f32_16x16x32_bf16 v[52:55], v[96:99], v[68:71], v[52:55]
	v_mfma_f32_16x16x32_bf16 v[40:43], v[104:107], v[68:71], v[40:43]
	v_mfma_f32_16x16x32_bf16 v[44:47], v[108:111], v[68:71], v[44:47]
	ds_read_b128 v[68:71], v0
	ds_read_b128 v[92:95], v0 offset:2048
	ds_read_b128 v[96:99], v137 offset:40960
	ds_read_b128 v[100:103], v137 offset:43008
	s_waitcnt lgkmcnt(3)
	v_mfma_f32_16x16x32_bf16 v[56:59], v[76:79], v[68:71], v[56:59]
	v_mfma_f32_16x16x32_bf16 v[60:63], v[88:91], v[68:71], v[60:63]
	s_waitcnt lgkmcnt(1)
	v_mfma_f32_16x16x32_bf16 v[104:107], v[96:99], v[68:71], v[112:115]
	s_waitcnt lgkmcnt(0)
	v_mfma_f32_16x16x32_bf16 v[48:51], v[100:103], v[68:71], v[48:51]
	ds_read_b128 v[68:71], v0 offset:4096
	ds_read_b128 v[108:111], v0 offset:6144
	s_nop 0
	v_and_b32_e32 v0, 15, v2
	v_ashrrev_i32_e32 v3, 1, v2
	v_mfma_f32_16x16x32_bf16 v[36:39], v[76:79], v[92:95], v[36:39]
	s_nop 1
	v_mul_f32_e32 v48, 0x43800000, v48
	v_mul_f32_e32 v49, 0x43800000, v49
	v_cvt_pk_fp8_f32 v119, v48, v49
	v_mfma_f32_16x16x32_bf16 v[32:35], v[88:91], v[92:95], v[32:35]
	v_mul_f32_e32 v50, 0x43800000, v50
	s_nop 0
	v_mul_f32_e32 v36, 0x43800000, v36
	v_mul_f32_e32 v37, 0x43800000, v37
	v_mfma_f32_16x16x32_bf16 v[28:31], v[96:99], v[92:95], v[28:31]
	v_cvt_pk_fp8_f32 v120, v36, v37
	s_nop 1
	v_mul_f32_e32 v32, 0x43800000, v32
	v_mul_f32_e32 v33, 0x43800000, v33
	v_mfma_f32_16x16x32_bf16 v[24:27], v[100:103], v[92:95], v[24:27]
	v_lshrrev_b32_e32 v92, 1, v2
	v_lshrrev_b32_e32 v93, 2, v2
	v_and_or_b32 v2, v3, s29, v0
	v_and_b32_e32 v0, 32, v92
	v_or_b32_e32 v92, 16, v2
	v_or_b32_e32 v94, 32, v2
	v_or_b32_e32 v112, 48, v2
	v_and_or_b32 v0, v93, 12, v0
	v_ashrrev_i32_e32 v3, 31, v2
	v_ashrrev_i32_e32 v93, 31, v92
	v_ashrrev_i32_e32 v95, 31, v94
	v_ashrrev_i32_e32 v113, 31, v112
	s_waitcnt lgkmcnt(1)
	v_mfma_f32_16x16x32_bf16 v[20:23], v[76:79], v[68:71], v[20:23]
	v_lshlrev_b64 v[2:3], 10, v[2:3]
	v_lshlrev_b64 v[92:93], 10, v[92:93]
	v_lshl_add_u64 v[2:3], s[0:1], 0, v[2:3]
	v_mfma_f32_16x16x32_bf16 v[80:83], v[88:91], v[68:71], v[80:83]
	v_lshl_add_u64 v[2:3], v[2:3], 0, v[0:1]
	v_mul_f32_e32 v28, 0x43800000, v28
	v_mul_f32_e32 v29, 0x43800000, v29
	v_mfma_f32_16x16x32_bf16 v[84:87], v[96:99], v[68:71], v[84:87]
	v_mul_f32_e32 v24, 0x43800000, v24
	v_mul_f32_e32 v25, 0x43800000, v25
	v_mul_f32_e32 v20, 0x43800000, v20
	v_mfma_f32_16x16x32_bf16 v[64:67], v[100:103], v[68:71], v[64:67]
	v_mul_f32_e32 v21, 0x43800000, v21
	v_mul_f32_e32 v80, 0x43800000, v80
	v_mul_f32_e32 v81, 0x43800000, v81
	s_waitcnt lgkmcnt(0)
; template <int MI>
; __device__ void gemm_tile_fp8out(const bf16_t* A, int lda, const bf16_t* B, int ldb, int K, unsigned char* C, int ldc, float mul, char* smem) {
;     ...
; #pragma unroll
;   for (int i = 0; i < MI; ++i)
; #pragma unroll
;     for (int j = 0; j < 4; ++j) {
;       int wd = __builtin_amdgcn_cvt_pk_fp8_f32(acc[i][j][0] * mul, acc[i][j][1] * mul, 0, false);
;       wd = __builtin_amdgcn_cvt_pk_fp8_f32(acc[i][j][2] * mul, acc[i][j][3] * mul, wd, true);
;       *(int*)(C + (size_t)MROW(i) * ldc + NCOL(j)) = wd;
;     }
	v_mfma_f32_16x16x32_bf16 v[68:71], v[76:79], v[108:111], v[72:75]
	v_lshl_add_u64 v[76:77], s[0:1], 0, v[92:93]
	v_lshl_add_u64 v[76:77], v[76:77], 0, v[0:1]
	v_mul_f32_e32 v78, 0x43800000, v105
	v_lshlrev_b64 v[72:73], 10, v[94:95]
	v_lshlrev_b64 v[74:75], 10, v[112:113]
	v_lshl_add_u64 v[72:73], s[0:1], 0, v[72:73]
	v_lshl_add_u64 v[74:75], s[0:1], 0, v[74:75]
	v_mfma_f32_16x16x32_bf16 v[52:55], v[88:91], v[108:111], v[52:55]
	v_lshl_add_u64 v[72:73], v[72:73], 0, v[0:1]
	v_lshl_add_u64 v[74:75], v[74:75], 0, v[0:1]
	v_mul_f32_e32 v0, 0x43800000, v56
	v_mfma_f32_16x16x32_bf16 v[40:43], v[96:99], v[108:111], v[40:43]
	v_mul_f32_e32 v56, 0x43800000, v57
	v_mul_f32_e32 v57, 0x43800000, v58
	v_mul_f32_e32 v58, 0x43800000, v59
	v_mfma_f32_16x16x32_bf16 v[44:47], v[100:103], v[108:111], v[44:47]
	v_mul_f32_e32 v59, 0x43800000, v60
	v_mul_f32_e32 v60, 0x43800000, v61
	v_cvt_pk_fp8_f32 v116, v0, v56
	v_mul_f32_e32 v61, 0x43800000, v62
	v_mul_f32_e32 v62, 0x43800000, v63
	v_mul_f32_e32 v63, 0x43800000, v104
	v_cvt_pk_fp8_f32 v117, v59, v60
	v_cvt_pk_fp8_f32 v118, v63, v78
	v_mul_f32_e32 v84, 0x43800000, v84
	v_mul_f32_e32 v85, 0x43800000, v85
	v_mul_f32_e32 v64, 0x43800000, v64
	v_mul_f32_e32 v65, 0x43800000, v65
	v_mul_f32_e32 v68, 0x43800000, v68
	v_mul_f32_e32 v69, 0x43800000, v69
	v_mul_f32_e32 v52, 0x43800000, v52
	v_mul_f32_e32 v53, 0x43800000, v53
	v_mul_f32_e32 v40, 0x43800000, v40
	v_mul_f32_e32 v41, 0x43800000, v41
	v_mul_f32_e32 v44, 0x43800000, v44
	v_mul_f32_e32 v45, 0x43800000, v45
	v_cvt_pk_fp8_f32 v121, v32, v33
	v_cvt_pk_fp8_f32 v122, v28, v29
	v_cvt_pk_fp8_f32 v123, v24, v25
	v_cvt_pk_fp8_f32 v124, v20, v21
	v_cvt_pk_fp8_f32 v125, v80, v81
	v_cvt_pk_fp8_f32 v126, v84, v85
	v_cvt_pk_fp8_f32 v127, v64, v65
	v_cvt_pk_fp8_f32 v128, v68, v69
	v_cvt_pk_fp8_f32 v129, v52, v53
	v_cvt_pk_fp8_f32 v130, v40, v41
	v_cvt_pk_fp8_f32 v131, v44, v45
	v_cvt_pk_fp8_f32 v116, v57, v58 op_sel:[0,0,1]
	v_mul_f32_e32 v79, 0x43800000, v106
	v_mul_f32_e32 v88, 0x43800000, v107
	v_cvt_pk_fp8_f32 v117, v61, v62 op_sel:[0,0,1]
	v_mul_f32_e32 v51, 0x43800000, v51
	v_cvt_pk_fp8_f32 v118, v79, v88 op_sel:[0,0,1]
	v_mul_f32_e32 v38, 0x43800000, v38
	v_mul_f32_e32 v39, 0x43800000, v39
	v_mul_f32_e32 v34, 0x43800000, v34
	v_mul_f32_e32 v35, 0x43800000, v35
	v_mul_f32_e32 v30, 0x43800000, v30
	v_mul_f32_e32 v31, 0x43800000, v31
	v_mul_f32_e32 v26, 0x43800000, v26
	v_mul_f32_e32 v27, 0x43800000, v27
	v_mul_f32_e32 v22, 0x43800000, v22
	v_mul_f32_e32 v23, 0x43800000, v23
	v_mul_f32_e32 v82, 0x43800000, v82
	v_mul_f32_e32 v83, 0x43800000, v83
	v_mul_f32_e32 v86, 0x43800000, v86
	v_mul_f32_e32 v87, 0x43800000, v87
	v_mul_f32_e32 v66, 0x43800000, v66
	v_mul_f32_e32 v67, 0x43800000, v67
	v_mul_f32_e32 v70, 0x43800000, v70
	v_mul_f32_e32 v71, 0x43800000, v71
	v_mul_f32_e32 v54, 0x43800000, v54
	v_mul_f32_e32 v55, 0x43800000, v55
	v_mul_f32_e32 v42, 0x43800000, v42
	v_mul_f32_e32 v43, 0x43800000, v43
	v_mul_f32_e32 v46, 0x43800000, v46
	v_mul_f32_e32 v47, 0x43800000, v47
	v_cvt_pk_fp8_f32 v119, v50, v51 op_sel:[0,0,1]
	v_cvt_pk_fp8_f32 v120, v38, v39 op_sel:[0,0,1]
	v_cvt_pk_fp8_f32 v121, v34, v35 op_sel:[0,0,1]
	v_cvt_pk_fp8_f32 v122, v30, v31 op_sel:[0,0,1]
	v_cvt_pk_fp8_f32 v123, v26, v27 op_sel:[0,0,1]
	v_cvt_pk_fp8_f32 v124, v22, v23 op_sel:[0,0,1]
	v_cvt_pk_fp8_f32 v125, v82, v83 op_sel:[0,0,1]
	v_cvt_pk_fp8_f32 v126, v86, v87 op_sel:[0,0,1]
	v_cvt_pk_fp8_f32 v127, v66, v67 op_sel:[0,0,1]
	v_cvt_pk_fp8_f32 v128, v70, v71 op_sel:[0,0,1]
	v_cvt_pk_fp8_f32 v129, v54, v55 op_sel:[0,0,1]
	v_cvt_pk_fp8_f32 v130, v42, v43 op_sel:[0,0,1]
	v_cvt_pk_fp8_f32 v131, v46, v47 op_sel:[0,0,1]
	global_store_dword v[2:3], v116, off
	global_store_dword v[2:3], v117, off offset:16
	global_store_dword v[2:3], v118, off offset:64
	global_store_dword v[2:3], v119, off offset:80
	global_store_dword v[76:77], v120, off
	global_store_dword v[76:77], v121, off offset:16
	global_store_dword v[76:77], v122, off offset:64
	global_store_dword v[76:77], v123, off offset:80
	global_store_dword v[72:73], v124, off
	global_store_dword v[72:73], v125, off offset:16
	global_store_dword v[72:73], v126, off offset:64
	global_store_dword v[72:73], v127, off offset:80
	global_store_dword v[74:75], v128, off
	global_store_dword v[74:75], v129, off offset:16
	global_store_dword v[74:75], v130, off offset:64
	global_store_dword v[74:75], v131, off offset:80
	s_cbranch_scc1 .LBB0_385
.Lfold_skip:
	s_mov_b32 s19, 0xc000
	s_movk_i32 s36, 0
